# MLA units prefetch the next MLA unit's tile-0 K/V LDS-DMA and Q loads at loop exit (batch+8, constant strides); next prologue masks its own copies with EXEC=0
# baseline (speedup 1.0000x reference)
.LBB0_125:
	s_add_u32 s12, s0, s2
	s_addc_u32 s13, s1, s3
	global_load_dwordx4 v[2:5], v185, s[12:13] offset:16
	global_load_dwordx4 v[6:9], v185, s[12:13]
	s_add_u32 s12, s6, s2
	s_addc_u32 s13, s7, s3
	global_load_dwordx4 v[10:13], v185, s[12:13] offset:16
	global_load_dwordx4 v[14:17], v185, s[12:13]
	s_add_u32 s12, s10, s2
	s_addc_u32 s13, s11, s3
	global_load_dwordx4 v[18:21], v185, s[12:13] offset:16
	global_load_dwordx4 v[22:25], v185, s[12:13]
	s_add_u32 s12, s4, s2
	s_addc_u32 s13, s5, s3
	global_load_dwordx4 v[26:29], v185, s[12:13] offset:16
	global_load_dwordx4 v[30:33], v185, s[12:13]
	s_add_u32 s2, s2, 32
	s_addc_u32 s3, s3, 0
	s_cmpk_eq_i32 s2, 0x100
	s_waitcnt vmcnt(0)
	v_mov_b32_e32 v34, v6
	v_mov_b32_e32 v6, v8
	s_waitcnt vmcnt(5)
	v_mov_b32_e32 v8, v10
	s_waitcnt vmcnt(4)
	v_mov_b32_e32 v36, v14
	v_mov_b32_e32 v14, v16
	s_waitcnt vmcnt(2)
	v_mov_b32_e32 v35, v22
	v_mov_b32_e32 v22, v7
	v_mov_b32_e32 v7, v24
	s_waitcnt vmcnt(0)
	v_mov_b32_e32 v37, v30
	v_pk_fma_f32 v[0:1], v[34:35], v[36:37], v[0:1]
	v_mov_b32_e32 v30, v15
	v_pk_fma_f32 v[0:1], v[22:23], v[30:31], v[0:1]
	v_mov_b32_e32 v15, v32
	v_pk_fma_f32 v[0:1], v[6:7], v[14:15], v[0:1]
	v_mov_b32_e32 v24, v9
	v_mov_b32_e32 v32, v17
	v_pk_fma_f32 v[0:1], v[24:25], v[32:33], v[0:1]
	v_mov_b32_e32 v6, v2
	v_mov_b32_e32 v7, v18
	v_mov_b32_e32 v9, v26
	v_pk_fma_f32 v[0:1], v[6:7], v[8:9], v[0:1]
	v_mov_b32_e32 v18, v3
	v_mov_b32_e32 v26, v11
	v_pk_fma_f32 v[0:1], v[18:19], v[26:27], v[0:1]
	v_mov_b32_e32 v2, v4
	v_mov_b32_e32 v3, v20
	v_mov_b32_e32 v6, v12
	v_mov_b32_e32 v7, v28
	v_pk_fma_f32 v[0:1], v[2:3], v[6:7], v[0:1]
	v_mov_b32_e32 v20, v5
	v_mov_b32_e32 v28, v13
	v_pk_fma_f32 v[0:1], v[20:21], v[28:29], v[0:1]
	s_cbranch_scc0 .LBB0_125
	v_readlane_b32 s0, v253, 18
	v_readlane_b32 s1, v253, 19
	s_andn2_b64 vcc, exec, s[0:1]
	s_cbranch_vccnz .LBB0_187
	v_readlane_b32 s0, v254, 54
	v_readlane_b32 s1, v254, 55
	v_mov_b32_e32 v2, 0x3eb60549
	v_mov_b32_e32 v3, 0x3e4ccccd
	v_cndmask_b32_e64 v2, v2, v3, s[0:1]
	s_lshl_b32 s0, s35, 7
	v_mul_f32_e32 v0, 0x3fb8aa3b, v0
	v_mul_f32_e32 v1, 0x3fb8aa3b, v1
	s_ashr_i32 s1, s0, 31
	v_exp_f32_e32 v0, v0
	v_exp_f32_e32 v1, v1
	s_lshl_b64 s[0:1], s[0:1], 2
	v_readlane_b32 s60, v254, 18
	v_readlane_b32 s61, v254, 19
	s_add_u32 s10, s60, s0
	s_addc_u32 s11, s61, s1
	v_readlane_b32 s0, v253, 20
	v_readlane_b32 s1, v253, 21
	s_add_u32 s0, s94, s0
	v_sub_f32_e32 v0, v0, v1
	s_addc_u32 s1, s95, s1
	v_add_f32_e32 v144, v2, v0
	v_readlane_b32 s62, v254, 20
	v_readlane_b32 s63, v254, 21
	s_add_u32 s12, s0, 0x3800000
	s_mov_b32 s62, 0x41380000
	s_movk_i32 s60, 0xc0
	s_addc_u32 s13, s1, 0
	v_sub_f32_e32 v157, 1.0, v2
	v_mov_b32_e32 v145, v144
	v_readlane_b32 s63, v253, 10
	v_readlane_b32 s64, v254, 22
	v_readlane_b32 s65, v254, 23
	v_readlane_b32 s66, v254, 24
	v_readlane_b32 s67, v254, 25
	v_readlane_b32 s68, v254, 26
	v_readlane_b32 s69, v254, 27
	v_readlane_b32 s70, v254, 28
	v_readlane_b32 s71, v254, 29
	v_readlane_b32 s72, v254, 30
	v_readlane_b32 s73, v254, 31
	v_readlane_b32 s74, v254, 32
	v_readlane_b32 s75, v254, 33
	s_mov_b32 s101, 0
	s_branch .LBB0_130

.LBB0_169:
	s_and_b32 s0, s64, 31
	s_lshl_b32 s0, s0, 6
	s_or_b32 s14, s14, s0
	s_mul_i32 s0, s15, 0x600
	s_mul_hi_u32 s1, s14, 0x600
	s_add_i32 s1, s1, s0
	s_mul_i32 s0, s14, 0x600
	s_add_u32 s0, s38, s0
	s_addc_u32 s1, s39, s1
	s_mul_hi_i32 s3, s2, 0xc0000
	s_mul_i32 s2, s2, 0xc0000
	v_mov_b32_e32 v158, v218
	s_add_u32 s4, s28, s2
	v_mov_b32_e32 v4, v218
	s_addc_u32 s5, s29, s3
	s_add_i32 s3, 0, 0x14000
	v_and_b32_e32 v0, 0x3fffffc0, v4
	v_lshl_add_u32 v159, v0, 2, s3
	v_ashrrev_i32_e32 v0, 6, v4
	v_and_b32_e32 v6, 31, v4
	v_readfirstlane_b32 s3, v0
	v_lshlrev_b32_e32 v0, 5, v0
	v_and_or_b32 v0, v0, 32, v6
	v_mul_u32_u24_e32 v0, 0x300, v0
	v_ashrrev_i32_e32 v2, 7, v4
	v_lshlrev_b32_e32 v184, 1, v0
	v_mul_lo_u32 v2, v2, s60
	v_lshl_add_u64 v[0:1], s[0:1], 0, v[184:185]
	v_ashrrev_i32_e32 v3, 31, v2
	v_lshl_add_u64 v[0:1], v[2:3], 1, v[0:1]
	v_lshrrev_b32_e32 v2, 1, v4
	v_and_b32_e32 v5, 63, v4
	v_and_b32_e32 v184, 16, v2
	v_lshl_add_u64 v[0:1], v[0:1], 0, v[184:185]
	s_lshl_b32 s6, s3, 10
	v_lshlrev_b32_e32 v3, 4, v5
	v_mov_b64_e32 v[248:249], v[0:1]
	s_cmp_eq_u32 s101, 1
	s_cselect_b64 exec, 0, -1
	global_load_dwordx4 v[96:99], v[0:1], off
	global_load_dwordx4 v[100:103], v[0:1], off offset:32
	global_load_dwordx4 v[104:107], v[0:1], off offset:64
	global_load_dwordx4 v[108:111], v[0:1], off offset:96
	global_load_dwordx4 v[112:115], v[0:1], off offset:128
	global_load_dwordx4 v[116:119], v[0:1], off offset:160
	global_load_dwordx4 v[120:123], v[0:1], off offset:192
	global_load_dwordx4 v[124:127], v[0:1], off offset:224
	global_load_dwordx4 v[128:131], v[0:1], off offset:256
	global_load_dwordx4 v[132:135], v[0:1], off offset:288
	global_load_dwordx4 v[136:139], v[0:1], off offset:320
	global_load_dwordx4 v[140:143], v[0:1], off offset:352
	s_mov_b64 exec, -1
	v_or_b32_e32 v0, s6, v3
	s_mov_b32 s0, 0x2aaaaaab
	v_mul_hi_i32 v1, v0, s0
	v_lshrrev_b32_e32 v7, 31, v1
	v_ashrrev_i32_e32 v1, 6, v1
	v_add_u32_e32 v1, v1, v7
	v_mul_i32_i24_e32 v7, 0x180, v1
	v_sub_u32_e32 v7, v0, v7
	v_ashrrev_i32_e32 v7, 4, v7
	v_lshrrev_b32_e32 v8, 1, v1
	v_bitop3_b32 v7, v8, v7, 7 bitop3:0x6c
	v_mul_i32_i24_e32 v1, 0xc0, v1
	v_lshl_add_u32 v146, v7, 3, v1
	v_add_u32_e32 v1, 0x2000, v0
	v_mul_hi_i32 v7, v1, s0
	v_lshrrev_b32_e32 v8, 31, v7
	v_ashrrev_i32_e32 v7, 6, v7
	v_add_u32_e32 v7, v7, v8
	v_mul_i32_i24_e32 v8, 0x180, v7
	v_sub_u32_e32 v1, v1, v8
	v_ashrrev_i32_e32 v1, 4, v1
	v_lshrrev_b32_e32 v8, 1, v7
	v_bitop3_b32 v1, v8, v1, 7 bitop3:0x6c
	v_mul_i32_i24_e32 v7, 0xc0, v7
	v_add_u32_e32 v0, 0x4000, v0
	v_lshl_add_u32 v148, v1, 3, v7
	v_mul_hi_i32 v1, v0, s0
	v_lshrrev_b32_e32 v7, 31, v1
	v_ashrrev_i32_e32 v1, 6, v1
	v_add_u32_e32 v1, v1, v7
	v_mul_i32_i24_e32 v7, 0x180, v1
	v_sub_u32_e32 v0, v0, v7
	v_ashrrev_i32_e32 v0, 4, v0
	v_lshrrev_b32_e32 v7, 1, v1
	v_bitop3_b32 v0, v7, v0, 7 bitop3:0x6c
	v_mul_i32_i24_e32 v1, 0xc0, v1
	v_lshlrev_b32_e32 v7, 3, v5
	s_lshl_b32 s0, s3, 6
	v_lshl_add_u32 v150, v0, 3, v1
	v_and_b32_e32 v1, 32, v4
	s_and_b32 s0, s0, 64
	v_and_b32_e32 v8, 24, v7
	v_or3_b32 v1, v8, v1, s0
	s_ashr_i32 s0, s6, 8
	s_and_b32 s1, s0, 0xfffff0
	s_lshr_b32 s0, s0, 1
	v_bfe_u32 v0, v4, 2, 2
	s_and_b32 s0, s0, 4
	v_and_or_b32 v0, v2, 8, v0
	s_or_b32 s0, s1, s0
	v_or_b32_e32 v8, s0, v0
	s_add_i32 s0, s6, 0x2000
	s_ashr_i32 s0, s0, 8
	s_lshl_b32 s2, s64, 2
	s_and_b32 s1, s0, 0xfffff0
	s_lshr_b32 s0, s0, 1
	s_and_b32 s2, s2, 28
	s_and_b32 s0, s0, 4
	s_or_b32 s0, s1, s0
	s_mulk_i32 s2, 0x6000
	v_or_b32_e32 v0, s0, v0
	s_add_u32 s0, s4, s2
	s_addc_u32 s1, s5, 0
	s_add_i32 s30, s6, 0
	v_ashrrev_i32_e32 v147, 31, v146
	v_mad_i32_i24 v152, v8, s60, v1
	v_mad_i32_i24 v154, v0, s60, v1
	s_add_i32 m0, s30, 0x8000
	v_lshl_add_u64 v[0:1], v[146:147], 1, s[0:1]
	v_ashrrev_i32_e32 v149, 31, v148
	s_waitcnt lgkmcnt(0)
	s_cmp_eq_u32 s101, 1
	s_cselect_b64 exec, 0, -1
	global_load_lds_dwordx4 v[0:1], off
	v_lshl_add_u64 v[0:1], v[148:149], 1, s[0:1]
	s_add_i32 m0, s30, 0xa000
	v_ashrrev_i32_e32 v151, 31, v150
	global_load_lds_dwordx4 v[0:1], off
	v_lshl_add_u64 v[0:1], v[150:151], 1, s[0:1]
	s_add_i32 m0, s30, 0xc000
	v_ashrrev_i32_e32 v153, 31, v152
	global_load_lds_dwordx4 v[0:1], off
	v_lshl_add_u64 v[0:1], v[152:153], 1, s[0:1]
	s_mov_b32 m0, s30
	v_ashrrev_i32_e32 v155, 31, v154
	global_load_lds_dwordx4 v[0:1], off
	v_lshl_add_u64 v[0:1], v[154:155], 1, s[0:1]
	s_add_i32 m0, s30, 0x2000
	s_cmp_lg_u32 0, -1
	global_load_lds_dwordx4 v[0:1], off
	s_mov_b64 exec, -1
	s_cselect_b32 s0, 0, 0
	s_add_i32 s1, s0, 0x8000
	v_lshlrev_b32_e32 v8, 1, v4
	v_lshlrev_b32_e32 v1, 3, v4
	v_mov_b32_e32 v4, s1
	s_movk_i32 s1, 0x180
	v_and_b32_e32 v1, 0x70, v1
	v_mad_u32_u24 v161, v6, s1, v4
	s_movk_i32 s1, 0x60
	v_and_b32_e32 v0, 32, v8
	v_bitop3_b32 v165, v184, v1, s1 bitop3:0x36
	s_movk_i32 s1, 0x118
	v_and_b32_e32 v3, 0xc0, v3
	v_and_or_b32 v0, v7, s1, v0
	v_add3_u32 v166, v3, s0, v0
	s_and_b32 s0, s64, 7
	v_mov_b32_e32 v14, v185
	v_mov_b32_e32 v15, v185
	v_bitop3_b32 v162, v2, v1, 16 bitop3:0x6c
	v_bitop3_b32 v163, v184, v1, 32 bitop3:0x36
	v_bitop3_b32 v164, v184, v1, 64 bitop3:0x36
	v_cmp_gt_u32_e64 s[6:7], 32, v5
	v_lshl_add_u32 v160, v6, 2, v159
	s_lshl_b32 s0, s0, 8
	v_mov_b32_e32 v0, v185
	v_mov_b32_e32 v1, v185
	v_mov_b32_e32 v2, v185
	v_mov_b32_e32 v3, v185
	v_mov_b32_e32 v4, v185
	v_mov_b32_e32 v5, v185
	v_mov_b32_e32 v6, v185
	v_mov_b32_e32 v7, v185
	v_mov_b32_e32 v8, v185
	v_mov_b32_e32 v9, v185
	v_mov_b32_e32 v10, v185
	v_mov_b32_e32 v11, v185
	v_mov_b32_e32 v12, v185
	v_mov_b32_e32 v13, v185
	v_mov_b64_e32 v[30:31], v[14:15]
	v_mov_b64_e32 v[46:47], v[14:15]
	v_mov_b64_e32 v[62:63], v[14:15]
	s_mov_b32 s31, 0
	s_or_b32 s34, s0, 64
	v_lshlrev_b32_e32 v212, 1, v146
	v_lshlrev_b32_e32 v213, 1, v148
	v_lshlrev_b32_e32 v214, 1, v150
	v_lshlrev_b32_e32 v215, 1, v152
	v_lshlrev_b32_e32 v216, 1, v154
	v_mov_b32_e32 v167, 0
	v_mov_b32_e32 v196, 0x80000000
	v_mov_b32_e32 v197, 0x80000000
	v_mov_b32_e32 v198, 0x80000000
	v_mov_b32_e32 v199, 0x80000000
	v_mov_b32_e32 v200, 0x80000000
	v_mov_b32_e32 v201, 0x80000000
	v_mov_b32_e32 v202, 0x80000000
	v_mov_b32_e32 v203, 0x80000000
	v_mov_b32_e32 v204, 0x80000000
	v_mov_b32_e32 v205, 0x80000000
	v_mov_b32_e32 v206, 0x80000000
	v_mov_b32_e32 v207, 0x80000000
	v_mov_b32_e32 v208, 0x80000000
	v_mov_b32_e32 v209, 0x80000000
	v_mov_b32_e32 v210, 0x80000000
	v_mov_b32_e32 v211, 0x80000000
	v_mov_b64_e32 v[28:29], v[12:13]
	v_mov_b64_e32 v[26:27], v[10:11]
	v_mov_b64_e32 v[24:25], v[8:9]
	v_mov_b64_e32 v[22:23], v[6:7]
	v_mov_b64_e32 v[20:21], v[4:5]
	v_mov_b64_e32 v[18:19], v[2:3]
	v_mov_b64_e32 v[16:17], v[0:1]
	v_mov_b64_e32 v[44:45], v[12:13]
	v_mov_b64_e32 v[42:43], v[10:11]
	v_mov_b64_e32 v[40:41], v[8:9]
	v_mov_b64_e32 v[38:39], v[6:7]
	v_mov_b64_e32 v[36:37], v[4:5]
	v_mov_b64_e32 v[34:35], v[2:3]
	v_mov_b64_e32 v[32:33], v[0:1]
	v_mov_b64_e32 v[60:61], v[12:13]
	v_mov_b64_e32 v[58:59], v[10:11]
	v_mov_b64_e32 v[56:57], v[8:9]
	v_mov_b64_e32 v[54:55], v[6:7]
	v_mov_b64_e32 v[52:53], v[4:5]
	v_mov_b64_e32 v[50:51], v[2:3]
	v_mov_b64_e32 v[48:49], v[0:1]
	v_mov_b32_e32 v168, 0
	s_waitcnt vmcnt(0) lgkmcnt(0)
	s_barrier
	s_and_b32 s35, s31, 1
	v_add_u32_e32 v156, v161, v162
	ds_read_b128 v[236:239], v156 offset:0
	ds_read_b128 v[240:243], v156 offset:0x3000
	s_cmp_eq_u32 s31, 31
	s_cbranch_scc1 .LBB0_171

.LBB0_185:
	s_add_i32 s0, s63, s81
	s_mov_b32 s101, 0
	s_cmp_ge_u32 s0, 0x600
	s_cbranch_scc1 .Lpfm_none
	s_mov_b32 s101, 1
	s_lshl_b32 s2, s64, 2
	s_and_b32 s2, s2, 28
	s_mulk_i32 s2, 0x6000
	s_add_u32 s0, s4, s2
	s_addc_u32 s1, s5, 0
	s_add_u32 s0, s0, 0x600000
	s_addc_u32 s1, s1, 0
	s_add_i32 m0, s30, 0x8000
	s_nop 0
	global_load_lds_dwordx4 v212, s[0:1]
	s_add_i32 m0, s30, 0xa000
	s_nop 0
	global_load_lds_dwordx4 v213, s[0:1]
	s_add_i32 m0, s30, 0xc000
	s_nop 0
	global_load_lds_dwordx4 v214, s[0:1]
	s_mov_b32 m0, s30
	s_nop 0
	global_load_lds_dwordx4 v215, s[0:1]
	s_add_i32 m0, s30, 0x2000
	s_nop 0
	global_load_lds_dwordx4 v216, s[0:1]
	s_mov_b32 s0, 0x1800000
	s_mov_b32 s1, 0
	v_lshl_add_u64 v[250:251], v[248:249], 0, s[0:1]
	global_load_dwordx4 v[96:99], v[250:251], off
	global_load_dwordx4 v[100:103], v[250:251], off offset:32
	global_load_dwordx4 v[104:107], v[250:251], off offset:64
	global_load_dwordx4 v[108:111], v[250:251], off offset:96
	global_load_dwordx4 v[112:115], v[250:251], off offset:128
	global_load_dwordx4 v[116:119], v[250:251], off offset:160
	global_load_dwordx4 v[120:123], v[250:251], off offset:192
	global_load_dwordx4 v[124:127], v[250:251], off offset:224
	global_load_dwordx4 v[128:131], v[250:251], off offset:256
	global_load_dwordx4 v[132:135], v[250:251], off offset:288
	global_load_dwordx4 v[136:139], v[250:251], off offset:320
	global_load_dwordx4 v[140:143], v[250:251], off offset:352
